# v021 + kvup tile prologue: two serialized B-operand loads batched with the other twelve
# speedup vs baseline: 1.0005x; 1.0005x over previous
; #define TIDX (tid_launder())
; #define G_STORE(ST, S, unused) do { char* d_ = smem + (ST) * STAGE; \
;     *(uint4*)(d_ + alo[0]) = S##a0; *(uint4*)(d_ + alo[1]) = S##a1; *(uint4*)(d_ + alo[2]) = S##a2; *(uint4*)(d_ + alo[3]) = S##a3; \
;     *(uint4*)(d_ + blo[0]) = S##b0; *(uint4*)(d_ + blo[1]) = S##b1; \
;     if (NBCH == 4) { *(uint4*)(d_ + blo[NBCH - 2]) = S##b2; *(uint4*)(d_ + blo[NBCH - 1]) = S##b3; } } while (0)
; template <int NJ, class RowA>
; DI void gemm_main(f32x16 (&acc)[2][NJ], const bf16_t* __restrict__ A, RowA rowA, size_t kstrideA, int m0, int Mmax,
;                   const bf16_t* __restrict__ Bt, size_t ldb, int n0, int nk, char* smem) {
;     ...
;   const int tid = TIDX, lane = tid & 63, wid = tid >> 6, wm = wid >> 1, wn = wid & 1;
;   const int r = lane & 31, hh = lane >> 5;
;   const bf16_t* ap[4]; const bf16_t* bp[NBCH]; int alo[4], blo[NBCH];
; #pragma unroll
;   for (int i = 0; i < 4; ++i) {
;     const int c = tid + 256 * i, row = c >> 3, kc = c & 7;
;     int m = m0 + row; m = m < Mmax ? m : Mmax - 1;
;     ap[i] = A + rowA(m) + kc * 8; alo[i] = row * 144 + kc * 16;
;   }
; #pragma unroll
;   for (int i = 0; i < NBCH; ++i) {
;     const int c = tid + 256 * i, row = c >> 3, kc = c & 7;
;     bp[i] = Bt + (size_t)(n0 + row) * ldb + kc * 8; blo[i] = 128 * 144 + row * 144 + kc * 16;
;   }
; #pragma unroll
;   for (int i = 0; i < 2; ++i)
; #pragma unroll
;     for (int j = 0; j < NJ; ++j)
; #pragma unroll
;       for (int e = 0; e < 16; ++e) acc[i][j][e] = 0.f;
;   uint4 x0a0, x0a1, x0a2, x0a3, x0b0, x0b1, x0b2, x0b3, x1a0, x1a1, x1a2, x1a3, x1b0, x1b1, x1b2, x1b3;
;   x0b2 = x0b3 = x1b2 = x1b3 = make_uint4(0, 0, 0, 0);
;     ...
;   __syncthreads();
;   G_LOAD(x0, 0, 0);
;   G_LOAD(x1, 0, 1);
;   G_STORE(0, x0, 0);
;   __syncthreads();
; DI void kvup_tile(const Params& p, int l, int mt, int tn, char* smem) {
;   f32x16 acc[2][2];
;   const int m0 = mt * 128;
;   gemm_main<2>(acc, p.projA + 512, RowLin{LDA_A}, 64, m0, T_TOK, p.wt_ukv, 128, tn * 128, 2, smem);
.LBB0_1251:
	s_cmp_gt_i32 s8, 63
	s_mov_b64 s[0:1], -1
	s_cbranch_scc0 .LBB0_1311
	s_sub_i32 s0, s8, 64
	v_mov_b32_e32 v38, v230
	s_lshl_b32 s1, s0, 5
	s_and_b32 s9, s8, 3
	s_waitcnt vmcnt(4)
	v_add_u32_e32 v11, 0x300, v38
	s_and_b32 s6, s1, 0x7fffff80
	v_lshlrev_b32_e32 v0, 4, v38
	v_readlane_b32 s16, v252, 57
	v_add_u32_e32 v4, 0x100, v38
	v_add_u32_e32 v6, 0x200, v38
	v_ashrrev_i32_e32 v14, 3, v11
	s_lshl_b32 s7, s9, 7
	v_and_b32_e32 v0, 0x70, v0
	v_readlane_b32 s17, v252, 58
	v_readlane_b32 s18, v252, 59
	v_readlane_b32 s19, v252, 60
	v_readlane_b32 s20, v252, 61
	v_readlane_b32 s21, v252, 62
	v_readlane_b32 s22, v252, 63
	v_readlane_b32 s23, v253, 0
	v_readlane_b32 s24, v253, 1
	v_readlane_b32 s25, v253, 2
	v_readlane_b32 s26, v253, 3
	v_readlane_b32 s27, v253, 4
	v_readlane_b32 s28, v253, 5
	v_readlane_b32 s29, v253, 6
	v_readlane_b32 s30, v253, 7
	v_readlane_b32 s31, v253, 8
	v_ashrrev_i32_e32 v10, 3, v38
	v_ashrrev_i32_e32 v12, 3, v4
	v_ashrrev_i32_e32 v13, 3, v6
	v_add_u32_e32 v11, s6, v14
	v_lshl_add_u64 v[8:9], s[24:25], 0, v[0:1]
	v_add_u32_e32 v2, s6, v10
	v_mad_u64_u32 v[114:115], s[4:5], v10, s76, v[0:1]
	v_add_u32_e32 v4, s6, v12
	v_add_u32_e32 v6, s6, v13
	v_min_i32_e32 v11, 0x7fff, v11
	v_readlane_b32 s16, v252, 9
	v_add_u32_e32 v10, s7, v10
	v_min_i32_e32 v2, 0x7fff, v2
	v_min_i32_e32 v4, 0x7fff, v4
	v_min_i32_e32 v6, 0x7fff, v6
	v_mad_i64_i32 v[32:33], s[4:5], v11, s50, v[8:9]
	v_readlane_b32 s26, v252, 19
	v_readlane_b32 s27, v252, 20
	v_ashrrev_i32_e32 v11, 31, v10
	v_mad_i64_i32 v[2:3], s[4:5], v2, s50, v[8:9]
	v_mad_i64_i32 v[4:5], s[4:5], v4, s50, v[8:9]
	v_mad_i64_i32 v[6:7], s[4:5], v6, s50, v[8:9]
	v_lshl_add_u64 v[8:9], s[26:27], 0, v[0:1]
	v_lshlrev_b64 v[10:11], 8, v[10:11]
	v_lshl_add_u64 v[34:35], v[8:9], 0, v[10:11]
	v_add_u32_e32 v10, s7, v12
	v_ashrrev_i32_e32 v11, 31, v10
	v_lshlrev_b64 v[10:11], 8, v[10:11]
	v_lshl_add_u64 v[36:37], v[8:9], 0, v[10:11]
	v_add_u32_e32 v10, s7, v13
	v_ashrrev_i32_e32 v11, 31, v10
	v_lshlrev_b64 v[10:11], 8, v[10:11]
	v_lshl_add_u64 v[124:125], v[8:9], 0, v[10:11]
	v_add_u32_e32 v10, s7, v14
	v_ashrrev_i32_e32 v11, 31, v10
	v_lshlrev_b64 v[10:11], 8, v[10:11]
	v_mad_u64_u32 v[116:117], s[4:5], v12, s76, v[0:1]
	v_mad_u64_u32 v[118:119], s[4:5], v13, s76, v[0:1]
	v_mad_u64_u32 v[120:121], s[4:5], v14, s76, v[0:1]
	v_lshl_add_u64 v[126:127], v[8:9], 0, v[10:11]
	s_barrier
	global_load_dwordx4 v[8:11], v[2:3], off offset:1024
	global_load_dwordx4 v[12:15], v[4:5], off offset:1024
	global_load_dwordx4 v[16:19], v[6:7], off offset:1024
	global_load_dwordx4 v[20:23], v[32:33], off offset:1024
	global_load_dwordx4 v[24:27], v[34:35], off
	global_load_dwordx4 v[28:31], v[36:37], off
	global_load_dwordx4 v[90:93], v[2:3], off offset:1152
	global_load_dwordx4 v[94:97], v[4:5], off offset:1152
	global_load_dwordx4 v[98:101], v[6:7], off offset:1152
	global_load_dwordx4 v[102:105], v[32:33], off offset:1152
	global_load_dwordx4 v[106:109], v[34:35], off offset:128
	global_load_dwordx4 v[110:113], v[36:37], off offset:128
	global_load_dwordx4 v[128:131], v[124:125], off
	global_load_dwordx4 v[132:135], v[126:127], off
	v_and_b32_e32 v39, 31, v38
	v_lshrrev_b32_e32 v0, 1, v38
	v_readlane_b32 s17, v252, 10
	v_readlane_b32 s18, v252, 11
	v_readlane_b32 s19, v252, 12
	v_readlane_b32 s20, v252, 13
	v_readlane_b32 s21, v252, 14
	v_readlane_b32 s22, v252, 15
	v_readlane_b32 s23, v252, 16
	s_waitcnt vmcnt(13)
	ds_write_b128 v114, v[8:11]
	s_waitcnt vmcnt(12)
	ds_write_b128 v116, v[12:15]
	s_waitcnt vmcnt(11)
	ds_write_b128 v118, v[16:19]
	s_waitcnt vmcnt(10)
	ds_write_b128 v120, v[20:23]
	s_waitcnt vmcnt(9)
	ds_write_b128 v114, v[24:27] offset:18432
	s_waitcnt vmcnt(8)
	ds_write_b128 v116, v[28:31] offset:18432
	v_readlane_b32 s24, v252, 17
	v_readlane_b32 s25, v252, 18
	v_readlane_b32 s28, v252, 21
	v_readlane_b32 s29, v252, 22
	v_readlane_b32 s30, v252, 23
	v_readlane_b32 s31, v252, 24
	s_waitcnt vmcnt(1)
	ds_write_b128 v118, v[128:131] offset:18432
	s_waitcnt vmcnt(0)
	ds_write_b128 v120, v[132:135] offset:18432
	global_load_dwordx4 v[128:131], v[126:127], off offset:128
	global_load_dwordx4 v[132:135], v[124:125], off offset:128
	s_waitcnt lgkmcnt(0)
	s_barrier
	global_load_dwordx4 v[66:69], v[2:3], off offset:1152
	global_load_dwordx4 v[70:73], v[4:5], off offset:1152
	global_load_dwordx4 v[74:77], v[6:7], off offset:1152
	global_load_dwordx4 v[78:81], v[32:33], off offset:1152
	global_load_dwordx4 v[82:85], v[34:35], off offset:128
	global_load_dwordx4 v[86:89], v[36:37], off offset:128
	v_and_or_b32 v8, v0, s47, v39
	v_and_b32_e32 v0, 16, v0
	v_and_b32_e32 v9, 0x5f, v38
	v_mad_u64_u32 v[122:123], s[4:5], v8, s76, v[0:1]
	v_mad_u32_u24 v0, v9, s76, v0
	s_setprio 1
	ds_read_b128 v[2:5], v122
	ds_read_b128 v[6:9], v0 offset:18432
	ds_read_b128 v[18:21], v0 offset:23040
	ds_read_b128 v[22:25], v122 offset:4608
	ds_read_b128 v[136:139], v122 offset:32
	ds_read_b128 v[140:143], v0 offset:18464
	ds_read_b128 v[144:147], v0 offset:23072
	s_waitcnt lgkmcnt(5)
	v_mfma_f32_32x32x16_bf16 v[34:49], v[2:5], v[6:9], 0
	s_waitcnt lgkmcnt(4)
	v_mfma_f32_32x32x16_bf16 v[50:65], v[2:5], v[18:21], 0
	s_waitcnt lgkmcnt(1)
	v_mfma_f32_32x32x16_bf16 v[34:49], v[136:139], v[140:143], v[34:49]
	s_waitcnt lgkmcnt(0)
	v_mfma_f32_32x32x16_bf16 v[50:65], v[136:139], v[144:147], v[50:65]
	ds_read_b128 v[136:139], v122 offset:4640
	v_mfma_f32_32x32x16_bf16 v[2:17], v[22:25], v[6:9], 0
	v_mfma_f32_32x32x16_bf16 v[18:33], v[22:25], v[18:21], 0
	s_waitcnt lgkmcnt(0)
	v_mfma_f32_32x32x16_bf16 v[2:17], v[136:139], v[140:143], v[2:17]
	v_mfma_f32_32x32x16_bf16 v[18:33], v[136:139], v[144:147], v[18:33]
	ds_read_b128 v[136:139], v122 offset:64
	ds_read_b128 v[140:143], v0 offset:18496
	ds_read_b128 v[144:147], v0 offset:23104
	s_waitcnt lgkmcnt(1)
; #define G_STORE(ST, S, unused) do { char* d_ = smem + (ST) * STAGE; \
;     *(uint4*)(d_ + alo[0]) = S##a0; *(uint4*)(d_ + alo[1]) = S##a1; *(uint4*)(d_ + alo[2]) = S##a2; *(uint4*)(d_ + alo[3]) = S##a3; \
;     *(uint4*)(d_ + blo[0]) = S##b0; *(uint4*)(d_ + blo[1]) = S##b1; \
;     if (NBCH == 4) { *(uint4*)(d_ + blo[NBCH - 2]) = S##b2; *(uint4*)(d_ + blo[NBCH - 1]) = S##b3; } } while (0)
; template <int NJ, class RowA>
; DI void gemm_main(f32x16 (&acc)[2][NJ], const bf16_t* __restrict__ A, RowA rowA, size_t kstrideA, int m0, int Mmax,
;                   const bf16_t* __restrict__ Bt, size_t ldb, int n0, int nk, char* smem) {
;     ...
; #pragma unroll 1
;   for (int kt = 0; kt < nk; kt += 2) {
;     G_LOAD(x0, 0, (kt + 2 < nk ? kt + 2 : nk - 1));
;     G_COMPUTE(0);
;     G_STORE(1, x1, 0);
;     __syncthreads();
;     G_LOAD(x1, 0, (kt + 3 < nk ? kt + 3 : nk - 1));
;     G_COMPUTE(1);
;     G_STORE(0, x0, 0);
;     __syncthreads();
;   }
	v_mfma_f32_32x32x16_bf16 v[34:49], v[136:139], v[140:143], v[34:49]
	s_waitcnt lgkmcnt(0)
	v_mfma_f32_32x32x16_bf16 v[50:65], v[136:139], v[144:147], v[50:65]
	ds_read_b128 v[136:139], v122 offset:4672
	s_waitcnt lgkmcnt(0)
	v_mfma_f32_32x32x16_bf16 v[2:17], v[136:139], v[140:143], v[2:17]
	v_mfma_f32_32x32x16_bf16 v[18:33], v[136:139], v[144:147], v[18:33]
	ds_read_b128 v[136:139], v122 offset:96
	ds_read_b128 v[140:143], v0 offset:18528
	ds_read_b128 v[144:147], v0 offset:23136
	s_waitcnt lgkmcnt(1)
	v_mfma_f32_32x32x16_bf16 v[34:49], v[136:139], v[140:143], v[34:49]
	s_waitcnt lgkmcnt(0)
	v_mfma_f32_32x32x16_bf16 v[50:65], v[136:139], v[144:147], v[50:65]
	ds_read_b128 v[136:139], v122 offset:4704
	s_waitcnt lgkmcnt(0)
	v_mfma_f32_32x32x16_bf16 v[2:17], v[136:139], v[140:143], v[2:17]
	v_mfma_f32_32x32x16_bf16 v[18:33], v[136:139], v[144:147], v[18:33]
	s_setprio 0
	ds_write_b128 v114, v[90:93] offset:36864
	ds_write_b128 v116, v[94:97] offset:36864
	ds_write_b128 v118, v[98:101] offset:36864
	ds_write_b128 v120, v[102:105] offset:36864
	ds_write_b128 v114, v[106:109] offset:55296
	ds_write_b128 v116, v[110:113] offset:55296
	s_waitcnt vmcnt(6)
	ds_write_b128 v118, v[132:135] offset:55296
	ds_write_b128 v120, v[128:131] offset:55296
	global_load_dwordx4 v[90:93], v[126:127], off offset:128
	global_load_dwordx4 v[94:97], v[124:125], off offset:128
	s_waitcnt lgkmcnt(0)
	s_barrier
	s_setprio 1
	ds_read_b128 v[98:101], v122 offset:36864
	ds_read_b128 v[102:105], v0 offset:55296
	ds_read_b128 v[106:109], v0 offset:59904
	s_waitcnt lgkmcnt(1)
	v_mfma_f32_32x32x16_bf16 v[34:49], v[98:101], v[102:105], v[34:49]
	s_waitcnt lgkmcnt(0)
	v_mfma_f32_32x32x16_bf16 v[50:65], v[98:101], v[106:109], v[50:65]
	ds_read_b128 v[98:101], v122 offset:41472
	s_waitcnt lgkmcnt(0)
	v_mfma_f32_32x32x16_bf16 v[2:17], v[98:101], v[102:105], v[2:17]
	v_mfma_f32_32x32x16_bf16 v[18:33], v[98:101], v[106:109], v[18:33]
	ds_read_b128 v[98:101], v122 offset:36896
	ds_read_b128 v[102:105], v0 offset:55328
	ds_read_b128 v[106:109], v0 offset:59936
	s_waitcnt lgkmcnt(1)
	v_mfma_f32_32x32x16_bf16 v[34:49], v[98:101], v[102:105], v[34:49]
	s_waitcnt lgkmcnt(0)
	v_mfma_f32_32x32x16_bf16 v[50:65], v[98:101], v[106:109], v[50:65]
	ds_read_b128 v[98:101], v122 offset:41504
	s_waitcnt lgkmcnt(0)
	v_mfma_f32_32x32x16_bf16 v[2:17], v[98:101], v[102:105], v[2:17]
	v_mfma_f32_32x32x16_bf16 v[18:33], v[98:101], v[106:109], v[18:33]
	ds_read_b128 v[98:101], v122 offset:36928
	ds_read_b128 v[102:105], v0 offset:55360
	ds_read_b128 v[106:109], v0 offset:59968
	s_waitcnt lgkmcnt(1)
	v_mfma_f32_32x32x16_bf16 v[34:49], v[98:101], v[102:105], v[34:49]
	s_waitcnt lgkmcnt(0)
	v_mfma_f32_32x32x16_bf16 v[50:65], v[98:101], v[106:109], v[50:65]
	ds_read_b128 v[98:101], v122 offset:41536
	s_waitcnt lgkmcnt(0)
	v_mfma_f32_32x32x16_bf16 v[2:17], v[98:101], v[102:105], v[2:17]
	v_mfma_f32_32x32x16_bf16 v[18:33], v[98:101], v[106:109], v[18:33]
	ds_read_b128 v[98:101], v122 offset:36960
	ds_read_b128 v[102:105], v0 offset:55392
	ds_read_b128 v[106:109], v0 offset:60000
	s_waitcnt lgkmcnt(1)
	v_mfma_f32_32x32x16_bf16 v[34:49], v[98:101], v[102:105], v[34:49]
	s_waitcnt lgkmcnt(0)
	v_mfma_f32_32x32x16_bf16 v[50:65], v[98:101], v[106:109], v[50:65]
	ds_read_b128 v[98:101], v122 offset:41568
	s_waitcnt lgkmcnt(0)
	v_mfma_f32_32x32x16_bf16 v[2:17], v[98:101], v[102:105], v[2:17]
	v_mfma_f32_32x32x16_bf16 v[18:33], v[98:101], v[106:109], v[18:33]
	s_setprio 0
	v_mov_b32_e32 v0, v230
	s_waitcnt vmcnt(7)
	ds_write_b128 v114, v[66:69]
	s_waitcnt vmcnt(6)
	ds_write_b128 v116, v[70:73]
	s_waitcnt vmcnt(5)
	ds_write_b128 v118, v[74:77]
	s_waitcnt vmcnt(4)
	ds_write_b128 v120, v[78:81]
	s_waitcnt vmcnt(3)
	ds_write_b128 v114, v[82:85] offset:18432
	s_waitcnt vmcnt(2)
	ds_write_b128 v116, v[86:89] offset:18432
	s_waitcnt vmcnt(0)
	ds_write_b128 v118, v[94:97] offset:18432
	ds_write_b128 v120, v[90:93] offset:18432
	s_waitcnt lgkmcnt(0)
	s_barrier
; #define TIDX (tid_launder())
; DI int crow(int reg, int hh) { return (reg & 3) + 8 * (reg >> 2) + 4 * hh; }
; template <int NJ>
; DI void acc_to_ct(const f32x16 (&acc)[2][NJ], float* Ct) {
;   const int lane = TIDX & 63, wid = TIDX >> 6, wm = wid >> 1, wn = wid & 1;
;   const int r = lane & 31, hh = lane >> 5;
; #pragma unroll
;   for (int i = 0; i < 2; ++i)
; #pragma unroll
;     for (int j = 0; j < NJ; ++j)
; #pragma unroll
;       for (int e = 0; e < 16; ++e) Ct[(wm * 64 + i * 32 + crow(e, hh)) * 132 + wn * 32 * NJ + j * 32 + r] = acc[i][j][e];
;   __syncthreads();
; DI void kvup_tile(const Params& p, int l, int mt, int tn, char* smem) {
;     ...
;   acc_to_ct<2>(acc, Ct);
;   const int b = m0 / SEQ, s0 = m0 % SEQ;
;   if (tn < 2) {
;     epi_rownorm(Ct, rn, 64);
;     const float* g = p.a_k_norm + l * 64;
;     epi_storeKF(Ct, 0, rn, 0, g, p.akv + (((size_t)b * 4 + tn * 2) * 64 + s0 / 32) * 2048);
;     epi_storeKF(Ct, 64, rn, 1, g, p.akv + (((size_t)b * 4 + tn * 2 + 1) * 64 + s0 / 32) * 2048);
;   } else {
;     const int h0 = (tn - 2) * 2;
	v_mov_b32_e32 v66, v230
	v_and_b32_e32 v67, 31, v0
	v_lshrrev_b32_e32 v0, 3, v0
	v_and_b32_e32 v0, 4, v0
	v_lshrrev_b32_e32 v68, 1, v66
	v_and_or_b32 v0, v68, s47, v0
	v_and_or_b32 v66, v66, 64, v67
	v_mul_lo_u32 v0, v0, s79
	v_lshl_add_u32 v0, v66, 2, v0
	ds_write2_b32 v0, v34, v50 offset1:32
	ds_write2_b32 v0, v35, v51 offset0:132 offset1:164
	v_add_u32_e32 v34, 0x400, v0
	ds_write2_b32 v34, v36, v52 offset0:8 offset1:40
	ds_write2_b32 v34, v37, v53 offset0:140 offset1:172
	v_add_u32_e32 v34, 0x1000, v0
	ds_write2_b32 v34, v38, v54 offset0:32 offset1:64
	ds_write2_b32 v34, v39, v55 offset0:164 offset1:196
	v_add_u32_e32 v34, 0x1400, v0
	ds_write2_b32 v34, v40, v56 offset0:40 offset1:72
	ds_write2_b32 v34, v41, v57 offset0:172 offset1:204
	v_add_u32_e32 v34, 0x2000, v0
	ds_write2_b32 v34, v42, v58 offset0:64 offset1:96
	ds_write2_b32 v34, v43, v59 offset0:196 offset1:228
	v_add_u32_e32 v34, 0x2400, v0
	ds_write2_b32 v34, v44, v60 offset0:72 offset1:104
	ds_write2_b32 v34, v45, v61 offset0:204 offset1:236
	v_add_u32_e32 v34, 0x3000, v0
	ds_write2_b32 v34, v46, v62 offset0:96 offset1:128
	v_add_u32_e32 v34, 0x3200, v0
	ds_write2_b32 v34, v47, v63 offset0:100 offset1:132
	v_add_u32_e32 v34, 0x3400, v0
	ds_write2_b32 v34, v48, v64 offset0:104 offset1:136
	v_add_u32_e32 v34, 0x3600, v0
	ds_write2_b32 v34, v49, v65 offset0:108 offset1:140
	v_add_u32_e32 v34, 0x4000, v0
	ds_write2_b32 v34, v2, v18 offset0:128 offset1:160
	v_add_u32_e32 v2, 0x4400, v0
	ds_write2_b32 v2, v3, v19 offset0:4 offset1:36
	ds_write2_b32 v2, v4, v20 offset0:136 offset1:168
	v_add_u32_e32 v2, 0x4800, v0
	ds_write2_b32 v2, v5, v21 offset0:12 offset1:44
	v_add_u32_e32 v2, 0x5000, v0
	ds_write2_b32 v2, v6, v22 offset0:160 offset1:192
	v_add_u32_e32 v2, 0x5400, v0
	ds_write2_b32 v2, v7, v23 offset0:36 offset1:68
	ds_write2_b32 v2, v8, v24 offset0:168 offset1:200
	v_add_u32_e32 v2, 0x5800, v0
	ds_write2_b32 v2, v9, v25 offset0:44 offset1:76
	v_add_u32_e32 v2, 0x6000, v0
	ds_write2_b32 v2, v10, v26 offset0:192 offset1:224
	v_add_u32_e32 v2, 0x6400, v0
	ds_write2_b32 v2, v11, v27 offset0:68 offset1:100
	ds_write2_b32 v2, v12, v28 offset0:200 offset1:232
	v_add_u32_e32 v2, 0x6800, v0
	ds_write2_b32 v2, v13, v29 offset0:76 offset1:108
	v_add_u32_e32 v2, 0x7200, v0
	ds_write2_b32 v2, v14, v30 offset0:96 offset1:128
	v_add_u32_e32 v2, 0x7400, v0
	s_lshr_b32 s11, s0, 6
	s_and_b32 s10, s1, 0x780
	ds_write2_b32 v2, v15, v31 offset0:100 offset1:132
	v_add_u32_e32 v2, 0x7600, v0
	v_add_u32_e32 v0, 0x7800, v0
	s_cmp_gt_u32 s9, 1
	s_mov_b64 s[0:1], -1
	ds_write2_b32 v2, v16, v32 offset0:104 offset1:136
	ds_write2_b32 v0, v17, v33 offset0:108 offset1:140
	s_waitcnt lgkmcnt(0)
	s_barrier
	s_cbranch_scc0 .LBB0_1260
	s_lshl_b32 s0, s9, 1
	s_lshl_b32 s1, s11, 2
	s_add_i32 s0, s0, s1
	s_add_i32 s14, s0, -4
	v_readlane_b32 s16, v250, 34
	s_lshl_b64 s[0:1], s[14:15], 18
	v_readlane_b32 s18, v250, 36
	v_readlane_b32 s19, v250, 37
	s_add_u32 s0, s18, s0
	s_addc_u32 s1, s19, s1
	s_lshl_b32 s4, s10, 7
	s_add_u32 s0, s0, s4
	v_mov_b32_e32 v4, v230
	s_movk_i32 s4, 0x400
	s_addc_u32 s1, s1, 0
	v_readlane_b32 s17, v250, 35
	v_cmp_gt_i32_e32 vcc, s4, v4
	v_readlane_b32 s20, v250, 38
	v_readlane_b32 s21, v250, 39
	v_readlane_b32 s22, v250, 40
	v_readlane_b32 s23, v250, 41
	v_readlane_b32 s24, v250, 42
	v_readlane_b32 s25, v250, 43
	v_readlane_b32 s26, v250, 44
	v_readlane_b32 s27, v250, 45
	v_readlane_b32 s28, v250, 46
	v_readlane_b32 s29, v250, 47
	v_readlane_b32 s30, v250, 48
	v_readlane_b32 s31, v250, 49
	s_and_saveexec_b64 s[4:5], vcc
	s_movk_i32 s14, 0x2ff
	s_cbranch_execz .LBB0_1256
	v_and_b32_e32 v0, 31, v4
	v_lshlrev_b32_e32 v2, 2, v0
	v_lshlrev_b32_e32 v3, 3, v4
	s_mov_b64 s[6:7], 0
